# hyena filter: 8-deep LDS read destination ring with counted lgkmcnt in the 64-step w3 broadcast-FMA loop (was ds_read + lgkmcnt(0) per step)
# speedup vs baseline: 1.0331x; 1.0261x over previous
; DI void phase_filter(const Params& p, int ch) {
;     ...
;     for (int c4 = 0; c4 < 16; ++c4) {
;       float a0 = 0.f, a1 = 0.f, a2 = 0.f, a3 = 0.f;
; #pragma unroll
;       for (int j = 0; j < 64; ++j) { f32x4 w = *(const f32x4*)(w3s + j * 64 + c4 * 4); a0 += hv[j] * w[0]; a1 += hv[j] * w[1]; a2 += hv[j] * w[2]; a3 += hv[j] * w[3]; }
;       float av[4] = {a0, a1, a2, a3};
; #pragma unroll
;       for (int i = 0; i < 4; ++i) { int cl = c4 * 4 + i; float delta = fabsf(mind + (float)(c0 + cl) * ((maxd - mind) / 2047.f)); float k = av[i] * __expf(-tl * delta);
;         float* row = kr + (size_t)(cc0 + cl) * N;
;         if (dir == 0) row[l] = k; else if (l > 0) row[N - l] = k; else row[L] = 0.f; }
.LBB0_1410:
	v_mov_b32_e32 v84, s14
	ds_read_b128 v[220:223], v84
	ds_read_b128 v[224:227], v84 offset:256
	ds_read_b128 v[228:231], v84 offset:512
	ds_read_b128 v[232:235], v84 offset:768
	ds_read_b128 v[236:239], v84 offset:1024
	ds_read_b128 v[244:247], v84 offset:1280
	ds_read_b128 v[248:251], v84 offset:1536
	ds_read_b128 v[80:83], v84 offset:1792
	s_add_i32 s15, s1, s20
	s_add_i32 s21, s37, s20
	s_lshl_b32 s96, s21, s0
	s_add_i32 s22, s15, 1
	s_waitcnt lgkmcnt(7)
	v_fma_f32 v78, v6, v220, 0
	v_fma_f32 v77, v6, v221, 0
	v_fma_f32 v76, v6, v222, 0
	v_fma_f32 v75, v6, v223, 0
	ds_read_b128 v[220:223], v84 offset:2048
	v_cvt_f32_u32_e32 v79, s15
	s_add_i32 s20, s20, 4
	s_waitcnt lgkmcnt(7)
	v_fmac_f32_e32 v78, v7, v224
	v_fmac_f32_e32 v77, v7, v225
	v_fmac_f32_e32 v76, v7, v226
	v_fmac_f32_e32 v75, v7, v227
	ds_read_b128 v[224:227], v84 offset:2304
	v_fmamk_f32 v79, v79, 0xbbc49550, v149
	v_mul_f32_e64 v79, v74, |v79|
	v_mul_f32_e32 v79, 0x3fb8aa3b, v79
	v_exp_f32_e32 v79, v79
	s_waitcnt lgkmcnt(7)
	v_fmac_f32_e32 v78, v12, v228
	v_fmac_f32_e32 v77, v12, v229
	v_fmac_f32_e32 v76, v12, v230
	v_fmac_f32_e32 v75, v12, v231
	ds_read_b128 v[228:231], v84 offset:2560
	s_add_i32 s14, s14, 16
	s_waitcnt lgkmcnt(7)
	v_fmac_f32_e32 v78, v13, v232
	v_fmac_f32_e32 v77, v13, v233
	v_fmac_f32_e32 v76, v13, v234
	v_fmac_f32_e32 v75, v13, v235
	ds_read_b128 v[232:235], v84 offset:2816
	s_waitcnt lgkmcnt(7)
	v_fmac_f32_e32 v78, v14, v236
	v_fmac_f32_e32 v77, v14, v237
	v_fmac_f32_e32 v76, v14, v238
	v_fmac_f32_e32 v75, v14, v239
	ds_read_b128 v[236:239], v84 offset:3072
	s_waitcnt lgkmcnt(7)
	v_fmac_f32_e32 v78, v15, v244
	v_fmac_f32_e32 v77, v15, v245
	v_fmac_f32_e32 v76, v15, v246
	v_fmac_f32_e32 v75, v15, v247
	ds_read_b128 v[244:247], v84 offset:3328
	s_waitcnt lgkmcnt(7)
	v_fmac_f32_e32 v78, v16, v248
	v_fmac_f32_e32 v77, v16, v249
	v_fmac_f32_e32 v76, v16, v250
	v_fmac_f32_e32 v75, v16, v251
	ds_read_b128 v[248:251], v84 offset:3584
	s_waitcnt lgkmcnt(7)
	v_fmac_f32_e32 v78, v17, v80
	v_fmac_f32_e32 v77, v17, v81
	v_fmac_f32_e32 v76, v17, v82
	v_fmac_f32_e32 v75, v17, v83
	ds_read_b128 v[80:83], v84 offset:3840
	s_waitcnt lgkmcnt(7)
	v_fmac_f32_e32 v78, v18, v220
	v_fmac_f32_e32 v77, v18, v221
	v_fmac_f32_e32 v76, v18, v222
	v_fmac_f32_e32 v75, v18, v223
	ds_read_b128 v[220:223], v84 offset:4096
	s_waitcnt lgkmcnt(7)
	v_fmac_f32_e32 v78, v19, v224
	v_fmac_f32_e32 v77, v19, v225
	v_fmac_f32_e32 v76, v19, v226
	v_fmac_f32_e32 v75, v19, v227
	ds_read_b128 v[224:227], v84 offset:4352
	s_waitcnt lgkmcnt(7)
	v_fmac_f32_e32 v78, v20, v228
	v_fmac_f32_e32 v77, v20, v229
	v_fmac_f32_e32 v76, v20, v230
	v_fmac_f32_e32 v75, v20, v231
	ds_read_b128 v[228:231], v84 offset:4608
	s_waitcnt lgkmcnt(7)
	v_fmac_f32_e32 v78, v21, v232
	v_fmac_f32_e32 v77, v21, v233
	v_fmac_f32_e32 v76, v21, v234
	v_fmac_f32_e32 v75, v21, v235
	ds_read_b128 v[232:235], v84 offset:4864
	s_waitcnt lgkmcnt(7)
	v_fmac_f32_e32 v78, v22, v236
	v_fmac_f32_e32 v77, v22, v237
	v_fmac_f32_e32 v76, v22, v238
	v_fmac_f32_e32 v75, v22, v239
	ds_read_b128 v[236:239], v84 offset:5120
	s_waitcnt lgkmcnt(7)
	v_fmac_f32_e32 v78, v23, v244
	v_fmac_f32_e32 v77, v23, v245
	v_fmac_f32_e32 v76, v23, v246
	v_fmac_f32_e32 v75, v23, v247
	ds_read_b128 v[244:247], v84 offset:5376
	s_waitcnt lgkmcnt(7)
	v_fmac_f32_e32 v78, v24, v248
	v_fmac_f32_e32 v77, v24, v249
	v_fmac_f32_e32 v76, v24, v250
	v_fmac_f32_e32 v75, v24, v251
	ds_read_b128 v[248:251], v84 offset:5632
	s_waitcnt lgkmcnt(7)
	v_fmac_f32_e32 v78, v25, v80
	v_fmac_f32_e32 v77, v25, v81
	v_fmac_f32_e32 v76, v25, v82
	v_fmac_f32_e32 v75, v25, v83
	ds_read_b128 v[80:83], v84 offset:5888
	s_waitcnt lgkmcnt(7)
	v_fmac_f32_e32 v78, v26, v220
	v_fmac_f32_e32 v77, v26, v221
	v_fmac_f32_e32 v76, v26, v222
	v_fmac_f32_e32 v75, v26, v223
	ds_read_b128 v[220:223], v84 offset:6144
	s_waitcnt lgkmcnt(7)
	v_fmac_f32_e32 v78, v27, v224
	v_fmac_f32_e32 v77, v27, v225
	v_fmac_f32_e32 v76, v27, v226
	v_fmac_f32_e32 v75, v27, v227
	ds_read_b128 v[224:227], v84 offset:6400
	s_waitcnt lgkmcnt(7)
	v_fmac_f32_e32 v78, v28, v228
	v_fmac_f32_e32 v77, v28, v229
	v_fmac_f32_e32 v76, v28, v230
	v_fmac_f32_e32 v75, v28, v231
	ds_read_b128 v[228:231], v84 offset:6656
	s_waitcnt lgkmcnt(7)
	v_fmac_f32_e32 v78, v29, v232
	v_fmac_f32_e32 v77, v29, v233
	v_fmac_f32_e32 v76, v29, v234
	v_fmac_f32_e32 v75, v29, v235
	ds_read_b128 v[232:235], v84 offset:6912
	s_waitcnt lgkmcnt(7)
	v_fmac_f32_e32 v78, v30, v236
	v_fmac_f32_e32 v77, v30, v237
	v_fmac_f32_e32 v76, v30, v238
	v_fmac_f32_e32 v75, v30, v239
	ds_read_b128 v[236:239], v84 offset:7168
	s_waitcnt lgkmcnt(7)
	v_fmac_f32_e32 v78, v31, v244
	v_fmac_f32_e32 v77, v31, v245
	v_fmac_f32_e32 v76, v31, v246
	v_fmac_f32_e32 v75, v31, v247
	ds_read_b128 v[244:247], v84 offset:7424
	s_waitcnt lgkmcnt(7)
	v_fmac_f32_e32 v78, v32, v248
	v_fmac_f32_e32 v77, v32, v249
	v_fmac_f32_e32 v76, v32, v250
	v_fmac_f32_e32 v75, v32, v251
	ds_read_b128 v[248:251], v84 offset:7680
	s_waitcnt lgkmcnt(7)
	v_fmac_f32_e32 v78, v33, v80
	v_fmac_f32_e32 v77, v33, v81
	v_fmac_f32_e32 v76, v33, v82
	v_fmac_f32_e32 v75, v33, v83
	ds_read_b128 v[80:83], v84 offset:7936
	s_waitcnt lgkmcnt(7)
	v_fmac_f32_e32 v78, v34, v220
	v_fmac_f32_e32 v77, v34, v221
	v_fmac_f32_e32 v76, v34, v222
	v_fmac_f32_e32 v75, v34, v223
	ds_read_b128 v[220:223], v84 offset:8192
	s_waitcnt lgkmcnt(7)
	v_fmac_f32_e32 v78, v35, v224
	v_fmac_f32_e32 v77, v35, v225
	v_fmac_f32_e32 v76, v35, v226
	v_fmac_f32_e32 v75, v35, v227
	ds_read_b128 v[224:227], v84 offset:8448
	s_waitcnt lgkmcnt(7)
	v_fmac_f32_e32 v78, v36, v228
	v_fmac_f32_e32 v77, v36, v229
	v_fmac_f32_e32 v76, v36, v230
	v_fmac_f32_e32 v75, v36, v231
	ds_read_b128 v[228:231], v84 offset:8704
	s_waitcnt lgkmcnt(7)
; DI void phase_filter(const Params& p, int ch) {
;     ...
; #pragma unroll
;       for (int j = 0; j < 64; ++j) { f32x4 w = *(const f32x4*)(w3s + j * 64 + c4 * 4); a0 += hv[j] * w[0]; a1 += hv[j] * w[1]; a2 += hv[j] * w[2]; a3 += hv[j] * w[3]; }
	v_fmac_f32_e32 v78, v37, v232
	v_fmac_f32_e32 v77, v37, v233
	v_fmac_f32_e32 v76, v37, v234
	v_fmac_f32_e32 v75, v37, v235
	ds_read_b128 v[232:235], v84 offset:8960
	s_waitcnt lgkmcnt(7)
	v_fmac_f32_e32 v78, v38, v236
	v_fmac_f32_e32 v77, v38, v237
	v_fmac_f32_e32 v76, v38, v238
	v_fmac_f32_e32 v75, v38, v239
	ds_read_b128 v[236:239], v84 offset:9216
	s_waitcnt lgkmcnt(7)
	v_fmac_f32_e32 v78, v39, v244
	v_fmac_f32_e32 v77, v39, v245
	v_fmac_f32_e32 v76, v39, v246
	v_fmac_f32_e32 v75, v39, v247
	ds_read_b128 v[244:247], v84 offset:9472
	s_waitcnt lgkmcnt(7)
	v_fmac_f32_e32 v78, v40, v248
	v_fmac_f32_e32 v77, v40, v249
	v_fmac_f32_e32 v76, v40, v250
	v_fmac_f32_e32 v75, v40, v251
	ds_read_b128 v[248:251], v84 offset:9728
	s_waitcnt lgkmcnt(7)
	v_fmac_f32_e32 v78, v41, v80
	v_fmac_f32_e32 v77, v41, v81
	v_fmac_f32_e32 v76, v41, v82
	v_fmac_f32_e32 v75, v41, v83
	ds_read_b128 v[80:83], v84 offset:9984
	s_waitcnt lgkmcnt(7)
	v_fmac_f32_e32 v78, v42, v220
	v_fmac_f32_e32 v77, v42, v221
	v_fmac_f32_e32 v76, v42, v222
	v_fmac_f32_e32 v75, v42, v223
	ds_read_b128 v[220:223], v84 offset:10240
	s_waitcnt lgkmcnt(7)
	v_fmac_f32_e32 v78, v43, v224
	v_fmac_f32_e32 v77, v43, v225
	v_fmac_f32_e32 v76, v43, v226
	v_fmac_f32_e32 v75, v43, v227
	ds_read_b128 v[224:227], v84 offset:10496
	s_waitcnt lgkmcnt(7)
	v_fmac_f32_e32 v78, v44, v228
	v_fmac_f32_e32 v77, v44, v229
	v_fmac_f32_e32 v76, v44, v230
	v_fmac_f32_e32 v75, v44, v231
	ds_read_b128 v[228:231], v84 offset:10752
	s_waitcnt lgkmcnt(7)
	v_fmac_f32_e32 v78, v45, v232
	v_fmac_f32_e32 v77, v45, v233
	v_fmac_f32_e32 v76, v45, v234
	v_fmac_f32_e32 v75, v45, v235
	ds_read_b128 v[232:235], v84 offset:11008
	s_waitcnt lgkmcnt(7)
	v_fmac_f32_e32 v78, v46, v236
	v_fmac_f32_e32 v77, v46, v237
	v_fmac_f32_e32 v76, v46, v238
	v_fmac_f32_e32 v75, v46, v239
	ds_read_b128 v[236:239], v84 offset:11264
	s_waitcnt lgkmcnt(7)
	v_fmac_f32_e32 v78, v47, v244
	v_fmac_f32_e32 v77, v47, v245
	v_fmac_f32_e32 v76, v47, v246
	v_fmac_f32_e32 v75, v47, v247
	ds_read_b128 v[244:247], v84 offset:11520
	s_waitcnt lgkmcnt(7)
	v_fmac_f32_e32 v78, v48, v248
	v_fmac_f32_e32 v77, v48, v249
	v_fmac_f32_e32 v76, v48, v250
	v_fmac_f32_e32 v75, v48, v251
	ds_read_b128 v[248:251], v84 offset:11776
	s_waitcnt lgkmcnt(7)
	v_fmac_f32_e32 v78, v49, v80
	v_fmac_f32_e32 v77, v49, v81
	v_fmac_f32_e32 v76, v49, v82
	v_fmac_f32_e32 v75, v49, v83
	ds_read_b128 v[80:83], v84 offset:12032
	s_waitcnt lgkmcnt(7)
	v_fmac_f32_e32 v78, v50, v220
	v_fmac_f32_e32 v77, v50, v221
	v_fmac_f32_e32 v76, v50, v222
	v_fmac_f32_e32 v75, v50, v223
	ds_read_b128 v[220:223], v84 offset:12288
	s_waitcnt lgkmcnt(7)
	v_fmac_f32_e32 v78, v51, v224
	v_fmac_f32_e32 v77, v51, v225
	v_fmac_f32_e32 v76, v51, v226
	v_fmac_f32_e32 v75, v51, v227
	ds_read_b128 v[224:227], v84 offset:12544
	s_waitcnt lgkmcnt(7)
	v_fmac_f32_e32 v78, v52, v228
	v_fmac_f32_e32 v77, v52, v229
	v_fmac_f32_e32 v76, v52, v230
	v_fmac_f32_e32 v75, v52, v231
	ds_read_b128 v[228:231], v84 offset:12800
	s_waitcnt lgkmcnt(7)
	v_fmac_f32_e32 v78, v53, v232
	v_fmac_f32_e32 v77, v53, v233
	v_fmac_f32_e32 v76, v53, v234
	v_fmac_f32_e32 v75, v53, v235
	ds_read_b128 v[232:235], v84 offset:13056
	s_waitcnt lgkmcnt(7)
	v_fmac_f32_e32 v78, v54, v236
	v_fmac_f32_e32 v77, v54, v237
	v_fmac_f32_e32 v76, v54, v238
	v_fmac_f32_e32 v75, v54, v239
	ds_read_b128 v[236:239], v84 offset:13312
	s_waitcnt lgkmcnt(7)
	v_fmac_f32_e32 v78, v55, v244
	v_fmac_f32_e32 v77, v55, v245
	v_fmac_f32_e32 v76, v55, v246
	v_fmac_f32_e32 v75, v55, v247
	ds_read_b128 v[244:247], v84 offset:13568
	s_waitcnt lgkmcnt(7)
	v_fmac_f32_e32 v78, v56, v248
	v_fmac_f32_e32 v77, v56, v249
	v_fmac_f32_e32 v76, v56, v250
	v_fmac_f32_e32 v75, v56, v251
	ds_read_b128 v[248:251], v84 offset:13824
	s_waitcnt lgkmcnt(7)
	v_fmac_f32_e32 v78, v57, v80
	v_fmac_f32_e32 v77, v57, v81
	v_fmac_f32_e32 v76, v57, v82
	v_fmac_f32_e32 v75, v57, v83
	ds_read_b128 v[80:83], v84 offset:14080
	s_waitcnt lgkmcnt(7)
	v_fmac_f32_e32 v78, v58, v220
	v_fmac_f32_e32 v77, v58, v221
	v_fmac_f32_e32 v76, v58, v222
	v_fmac_f32_e32 v75, v58, v223
	ds_read_b128 v[220:223], v84 offset:14336
	s_waitcnt lgkmcnt(7)
; DI void phase_filter(const Params& p, int ch) {
;     ...
;       for (int j = 0; j < 64; ++j) { f32x4 w = *(const f32x4*)(w3s + j * 64 + c4 * 4); a0 += hv[j] * w[0]; a1 += hv[j] * w[1]; a2 += hv[j] * w[2]; a3 += hv[j] * w[3]; }
;       float av[4] = {a0, a1, a2, a3};
; #pragma unroll
;       for (int i = 0; i < 4; ++i) { int cl = c4 * 4 + i; float delta = fabsf(mind + (float)(c0 + cl) * ((maxd - mind) / 2047.f)); float k = av[i] * __expf(-tl * delta);
;         float* row = kr + (size_t)(cc0 + cl) * N;
;         if (dir == 0) row[l] = k; else if (l > 0) row[N - l] = k; else row[L] = 0.f; }
;     }
;     __syncthreads();
;   }
	v_fmac_f32_e32 v78, v59, v224
	v_fmac_f32_e32 v77, v59, v225
	v_fmac_f32_e32 v76, v59, v226
	v_fmac_f32_e32 v75, v59, v227
	ds_read_b128 v[224:227], v84 offset:14592
	s_waitcnt lgkmcnt(7)
	v_fmac_f32_e32 v78, v60, v228
	v_fmac_f32_e32 v77, v60, v229
	v_fmac_f32_e32 v76, v60, v230
	v_fmac_f32_e32 v75, v60, v231
	ds_read_b128 v[228:231], v84 offset:14848
	s_waitcnt lgkmcnt(7)
	v_fmac_f32_e32 v78, v61, v232
	v_fmac_f32_e32 v77, v61, v233
	v_fmac_f32_e32 v76, v61, v234
	v_fmac_f32_e32 v75, v61, v235
	ds_read_b128 v[232:235], v84 offset:15104
	s_waitcnt lgkmcnt(7)
	v_fmac_f32_e32 v78, v62, v236
	v_fmac_f32_e32 v77, v62, v237
	v_fmac_f32_e32 v76, v62, v238
	v_fmac_f32_e32 v75, v62, v239
	ds_read_b128 v[236:239], v84 offset:15360
	s_waitcnt lgkmcnt(7)
	v_fmac_f32_e32 v78, v63, v244
	v_fmac_f32_e32 v77, v63, v245
	v_fmac_f32_e32 v76, v63, v246
	v_fmac_f32_e32 v75, v63, v247
	ds_read_b128 v[244:247], v84 offset:15616
	s_waitcnt lgkmcnt(7)
	v_fmac_f32_e32 v78, v64, v248
	v_fmac_f32_e32 v77, v64, v249
	v_fmac_f32_e32 v76, v64, v250
	v_fmac_f32_e32 v75, v64, v251
	ds_read_b128 v[248:251], v84 offset:15872
	s_waitcnt lgkmcnt(7)
	v_fmac_f32_e32 v78, v65, v80
	v_fmac_f32_e32 v77, v65, v81
	v_fmac_f32_e32 v76, v65, v82
	v_fmac_f32_e32 v75, v65, v83
	ds_read_b128 v[80:83], v84 offset:16128
	s_waitcnt lgkmcnt(7)
	v_fmac_f32_e32 v78, v66, v220
	v_fmac_f32_e32 v77, v66, v221
	v_fmac_f32_e32 v76, v66, v222
	v_fmac_f32_e32 v75, v66, v223
	s_waitcnt lgkmcnt(6)
	v_fmac_f32_e32 v78, v67, v224
	v_fmac_f32_e32 v77, v67, v225
	v_fmac_f32_e32 v76, v67, v226
	v_fmac_f32_e32 v75, v67, v227
	s_waitcnt lgkmcnt(5)
	v_fmac_f32_e32 v78, v68, v228
	v_fmac_f32_e32 v77, v68, v229
	v_fmac_f32_e32 v76, v68, v230
	v_fmac_f32_e32 v75, v68, v231
	s_waitcnt lgkmcnt(4)
	v_fmac_f32_e32 v78, v69, v232
	v_fmac_f32_e32 v77, v69, v233
	v_fmac_f32_e32 v76, v69, v234
	v_fmac_f32_e32 v75, v69, v235
	s_waitcnt lgkmcnt(3)
	v_fmac_f32_e32 v78, v70, v236
	v_fmac_f32_e32 v77, v70, v237
	v_fmac_f32_e32 v76, v70, v238
	v_fmac_f32_e32 v75, v70, v239
	s_waitcnt lgkmcnt(2)
	v_fmac_f32_e32 v78, v71, v244
	v_fmac_f32_e32 v77, v71, v245
	v_fmac_f32_e32 v76, v71, v246
	v_fmac_f32_e32 v75, v71, v247
	s_waitcnt lgkmcnt(1)
	v_fmac_f32_e32 v78, v72, v248
	v_fmac_f32_e32 v77, v72, v249
	v_fmac_f32_e32 v76, v72, v250
	v_fmac_f32_e32 v75, v72, v251
	s_waitcnt lgkmcnt(0)
	v_fmac_f32_e32 v78, v73, v80
	v_mul_f32_e32 v78, v79, v78
	v_cndmask_b32_e32 v80, 0, v78, vcc
	v_lshl_add_u64 v[78:79], s[96:97], 2, v[4:5]
	global_store_dword v[78:79], v80, off
	v_cvt_f32_u32_e32 v78, s22
	v_fmac_f32_e32 v77, v73, v81
	s_add_i32 s22, s21, 1
	s_lshl_b32 s96, s22, s0
	v_fmamk_f32 v78, v78, 0xbbc49550, v149
	v_mul_f32_e64 v78, v74, |v78|
	v_mul_f32_e32 v78, 0x3fb8aa3b, v78
	v_exp_f32_e32 v78, v78
	s_add_i32 s22, s15, 2
	v_fmac_f32_e32 v76, v73, v82
	s_add_i32 s15, s15, 3
	v_mul_f32_e32 v77, v78, v77
	v_cndmask_b32_e32 v77, 0, v77, vcc
	v_lshl_add_u64 v[78:79], s[96:97], 2, v[4:5]
	global_store_dword v[78:79], v77, off
	v_cvt_f32_u32_e32 v77, s22
	s_add_i32 s22, s21, 2
	s_lshl_b32 s96, s22, s0
	v_fmac_f32_e32 v75, v73, v83
	v_fmamk_f32 v77, v77, 0xbbc49550, v149
	v_mul_f32_e64 v77, v74, |v77|
	v_mul_f32_e32 v77, 0x3fb8aa3b, v77
	v_exp_f32_e32 v77, v77
	s_add_i32 s21, s21, 3
	v_mul_f32_e32 v76, v77, v76
	v_cndmask_b32_e32 v78, 0, v76, vcc
	v_lshl_add_u64 v[76:77], s[96:97], 2, v[4:5]
	global_store_dword v[76:77], v78, off
	v_cvt_f32_u32_e32 v76, s15
	s_lshl_b32 s96, s21, s0
	s_cmp_lg_u32 s20, 64
	v_fmamk_f32 v76, v76, 0xbbc49550, v149
	v_mul_f32_e64 v76, v74, |v76|
	v_mul_f32_e32 v76, 0x3fb8aa3b, v76
	v_exp_f32_e32 v76, v76
	s_nop 0
	v_mul_f32_e32 v75, v76, v75
	v_cndmask_b32_e32 v75, 0, v75, vcc
	v_lshl_add_u64 v[76:77], s[96:97], 2, v[4:5]
	global_store_dword v[76:77], v75, off
	s_cbranch_scc1 .LBB0_1410
	s_add_i32 s36, s36, s28
	s_cmpk_lt_i32 s36, 0xc0
	s_barrier
	s_cbranch_scc1 .LBB0_1399
	v_readlane_b32 s38, v240, 53
	v_readlane_b32 s39, v240, 54
	s_mov_b32 s36, s70
